# attention work queue: static s_setprio 1 for waves 0..3 (one wave of each SIMD pair) while units run, reset after the queue (asm guide 7.4); plus attention packed->scalar split
# baseline (speedup 1.0000x reference)
.LBB0_363:
	v_readfirstlane_b32 s2, v196
	s_cmp_ge_u32 s2, 0x100
	s_cbranch_scc1 .Lattn_prio_done
	s_setprio 1
